# P3 loop: persistent K address bases, slot offset reused by the DMA block, mask check against a per-unit bound
# baseline (speedup 1.0000x reference)
.LBB0_318:
	s_or_b32 s0, s78, 31
	s_or_b32 s1, s2, 64
	s_cmp_gt_u32 s1, s0
	s_cselect_b64 s[70:71], -1, 0
	s_cmp_lg_u64 s[70:71], 0
	s_subb_u32 s82, s33, 0
	s_sub_i32 s0, s72, s2
	v_cvt_f32_i32_e32 v38, s0
	v_lshrrev_b32_e32 v35, 2, v35
	v_lshlrev_b32_e32 v45, 1, v211
	v_and_b32_e32 v44, 12, v33
	v_fma_f32 v40, v208, v38, -v207
	v_fmamk_f32 v41, v208, 0x42000000, v40
	v_add_f32_e32 v16, v40, v16
	v_add_f32_e32 v0, v41, v0
	v_exp_f32_e32 v42, v16
	v_exp_f32_e32 v43, v0
	v_add_f32_e32 v0, v40, v17
	v_add_f32_e32 v1, v41, v1
	v_exp_f32_e32 v0, v0
	v_exp_f32_e32 v16, v1
	v_add_f32_e32 v17, v43, v42
	v_mov_b32_e32 v1, v113
	v_add_f32_e32 v2, v41, v2
	v_pk_add_f32 v[38:39], v[16:17], v[0:1]
	v_add_f32_e32 v1, v40, v18
	v_pk_add_f32 v[38:39], v[38:39], v[38:39] op_sel_hi:[0,1]
	v_exp_f32_e32 v17, v2
	v_add_f32_e32 v2, v40, v19
	v_exp_f32_e32 v1, v1
	v_exp_f32_e32 v38, v2
	v_add_f32_e32 v2, v41, v3
	v_exp_f32_e32 v2, v2
	v_add_f32_e32 v3, v17, v1
	v_add_f32_e32 v4, v41, v4
	v_add_f32_e32 v6, v41, v6
	v_pk_add_f32 v[18:19], v[2:3], v[38:39]
	v_add_f32_e32 v3, v40, v20
	v_pk_add_f32 v[18:19], v[18:19], v[18:19] op_sel_hi:[0,1]
	v_exp_f32_e32 v39, v4
	v_add_f32_e32 v4, v40, v21
	v_exp_f32_e32 v3, v3
	v_exp_f32_e32 v18, v4
	v_add_f32_e32 v4, v41, v5
	v_exp_f32_e32 v4, v4
	v_or_b32_e32 v5, v34, v35
	v_lshlrev_b32_e32 v35, 8, v5
	v_add_f32_e32 v5, v39, v3
	v_pk_add_f32 v[20:21], v[4:5], v[18:19]
	v_add_f32_e32 v5, v40, v22
	v_pk_add_f32 v[20:21], v[20:21], v[20:21] op_sel_hi:[0,1]
	v_exp_f32_e32 v19, v6
	v_add_f32_e32 v6, v40, v23
	v_exp_f32_e32 v5, v5
	v_exp_f32_e32 v20, v6
	v_add_f32_e32 v6, v41, v7
	v_exp_f32_e32 v6, v6
	v_add_f32_e32 v7, v19, v5
	v_add_f32_e32 v8, v41, v8
	v_add_f32_e32 v10, v41, v10
	v_pk_add_f32 v[22:23], v[6:7], v[20:21]
	v_add_f32_e32 v7, v40, v24
	v_pk_add_f32 v[22:23], v[22:23], v[22:23] op_sel_hi:[0,1]
	v_exp_f32_e32 v21, v8
	v_add_f32_e32 v8, v40, v25
	v_exp_f32_e32 v7, v7
	v_exp_f32_e32 v22, v8
	v_add_f32_e32 v8, v41, v9
	v_exp_f32_e32 v8, v8
	v_add_f32_e32 v9, v21, v7
	v_and_b32_e32 v45, 2, v45
	v_and_b32_e32 v37, 1, v37
	v_pk_add_f32 v[24:25], v[8:9], v[22:23]
	v_add_f32_e32 v9, v40, v26
	v_pk_add_f32 v[24:25], v[24:25], v[24:25] op_sel_hi:[0,1]
	v_exp_f32_e32 v23, v10
	v_add_f32_e32 v10, v40, v27
	v_exp_f32_e32 v9, v9
	v_exp_f32_e32 v24, v10
	v_add_f32_e32 v10, v41, v11
	v_exp_f32_e32 v10, v10
	v_or3_b32 v11, v44, v45, v37
	v_lshlrev_b32_e32 v37, 4, v11
	v_add_f32_e32 v11, v23, v9
	v_pk_add_f32 v[26:27], v[10:11], v[24:25]
	v_add_f32_e32 v12, v41, v12
	v_pk_add_f32 v[26:27], v[26:27], v[26:27] op_sel_hi:[0,1]
	v_add_f32_e32 v11, v40, v28
	v_exp_f32_e32 v25, v12
	v_add_f32_e32 v12, v40, v29
	v_exp_f32_e32 v11, v11
	v_exp_f32_e32 v26, v12
	v_add_f32_e32 v12, v41, v13
	v_exp_f32_e32 v12, v12
	v_lshlrev_b32_e32 v13, 3, v33
	v_and_b32_e32 v33, 8, v13
	v_add_f32_e32 v13, v25, v11
	v_pk_add_f32 v[28:29], v[12:13], v[26:27]
	v_add_f32_e32 v14, v41, v14
	v_pk_add_f32 v[28:29], v[28:29], v[28:29] op_sel_hi:[0,1]
	v_add_f32_e32 v13, v40, v30
	v_exp_f32_e32 v27, v14
	v_add_f32_e32 v14, v40, v31
	v_exp_f32_e32 v13, v13
	v_exp_f32_e32 v28, v14
	v_add_f32_e32 v14, v41, v15
	v_exp_f32_e32 v14, v14
	v_add_f32_e32 v15, v27, v13
	v_or3_b32 v235, v37, v35, v33
	s_mov_b32 s72, 0
	v_pk_add_f32 v[30:31], v[14:15], v[28:29]
	v_cvt_pk_bf16_f32 v152, v42, v0
	v_cvt_pk_bf16_f32 v153, v1, v38
	v_cvt_pk_bf16_f32 v154, v3, v18
	v_cvt_pk_bf16_f32 v155, v5, v20
	v_cvt_pk_bf16_f32 v156, v7, v22
	s_nop 0
	v_add_f32_e32 v15, v30, v31
	v_add_f32_e32 v229, 0, v15
	v_cvt_pk_bf16_f32 v157, v9, v24
	v_cvt_pk_bf16_f32 v158, v11, v26
	v_cvt_pk_bf16_f32 v159, v13, v28
	v_cvt_pk_bf16_f32 v148, v43, v16
	v_cvt_pk_bf16_f32 v149, v17, v2
	v_cvt_pk_bf16_f32 v150, v39, v4
	v_cvt_pk_bf16_f32 v151, v19, v6
	v_cvt_pk_bf16_f32 v160, v21, v8
	v_cvt_pk_bf16_f32 v161, v23, v10
	v_cvt_pk_bf16_f32 v162, v25, v12
	v_cvt_pk_bf16_f32 v163, v27, v14
	s_cmp_lt_i32 s82, 2
	v_xor_b32_e32 v236, 0x80, v235
	v_xor_b32_e32 v234, 0xc0, v235
	s_cbranch_scc1 .LBB0_331
	s_mov_b32 s97, s83
	s_lshl_b64 s[0:1], s[96:97], 13
	v_lshl_add_u64 v[0:1], v[212:213], 0, s[0:1]
	s_mov_b64 s[0:1], 0x106000
	v_lshl_add_u64 v[218:219], v[0:1], 0, s[0:1]
	s_mov_b64 s[0:1], 0x6000
	v_lshl_add_u64 v[220:221], v[0:1], 0, s[0:1]
	s_lshl_b64 s[0:1], s[96:97], 14
	v_lshl_add_u64 v[0:1], v[214:215], 0, s[0:1]
	s_mov_b64 s[4:5], 0xc000
	v_lshl_add_u64 v[222:223], v[0:1], 0, s[4:5]
	v_lshl_add_u64 v[0:1], v[216:217], 0, s[0:1]
	v_readlane_b32 s1, v244, 25
	s_add_i32 s1, s1, s2
	v_lshl_add_u64 v[224:225], v[0:1], 0, s[4:5]
	v_add_u32_e32 v0, s1, v32
	s_lshl_b32 s0, s96, 6
	v_sub_u32_e32 v0, v0, v34
	s_add_i32 s97, s0, 0x7f
	v_subrev_u32_e32 v240, s0, v0
	s_and_b32 s0, s74, 63
	s_lshl_b32 s0, s0, 7
	v_mov_b32_e32 v0, 0
	v_mul_f32_e32 v237, 0x42000000, v208
	v_add_u32_e32 v238, 0, v36
	v_xor_b32_e32 v239, 64, v235
	s_add_i32 s73, s33, -2
	s_add_i32 s79, s77, 0x18000
	s_sub_i32 s74, 0, s0
	v_mov_b32_e32 v1, v0
	v_mov_b32_e32 v2, v0
	v_mov_b32_e32 v3, v0
	v_mov_b32_e32 v4, v0
	v_mov_b32_e32 v5, v0
	v_mov_b32_e32 v6, v0
	v_mov_b32_e32 v7, v0
	v_mov_b32_e32 v8, v0
	v_mov_b32_e32 v9, v0
	v_mov_b32_e32 v10, v0
	v_mov_b32_e32 v11, v0
	v_mov_b32_e32 v12, v0
	v_mov_b32_e32 v13, v0
	v_mov_b32_e32 v14, v0
	v_mov_b32_e32 v15, v0
	v_mov_b32_e32 v16, v0
	v_mov_b32_e32 v17, v0
	v_mov_b32_e32 v18, v0
	v_mov_b32_e32 v19, v0
	v_mov_b32_e32 v20, v0
	v_mov_b32_e32 v21, v0
	v_mov_b32_e32 v22, v0
	v_mov_b32_e32 v23, v0
	v_mov_b32_e32 v24, v0
	v_mov_b32_e32 v25, v0
	v_mov_b32_e32 v26, v0
	v_mov_b32_e32 v27, v0
	v_mov_b32_e32 v28, v0
	v_mov_b32_e32 v29, v0
	v_mov_b32_e32 v30, v0
	v_mov_b32_e32 v31, v0
	v_mov_b32_e32 v32, v0
	v_mov_b32_e32 v33, v0
	v_mov_b32_e32 v34, v0
	v_mov_b32_e32 v35, v0
	v_mov_b32_e32 v36, v0
	v_mov_b32_e32 v37, v0
	v_mov_b32_e32 v38, v0
	v_mov_b32_e32 v39, v0
	v_mov_b32_e32 v40, v0
	v_mov_b32_e32 v41, v0
	v_mov_b32_e32 v42, v0
	v_mov_b32_e32 v43, v0
	v_mov_b32_e32 v44, v0
	v_mov_b32_e32 v45, v0
	v_mov_b32_e32 v46, v0
	v_mov_b32_e32 v47, v0
	v_mov_b32_e32 v48, v0
	v_mov_b32_e32 v49, v0
	v_mov_b32_e32 v50, v0
	v_mov_b32_e32 v51, v0
	v_mov_b32_e32 v52, v0
	v_mov_b32_e32 v53, v0
	v_mov_b32_e32 v54, v0
	v_mov_b32_e32 v55, v0
	v_mov_b32_e32 v56, v0
	v_mov_b32_e32 v57, v0
	v_mov_b32_e32 v58, v0
	v_mov_b32_e32 v59, v0
	v_mov_b32_e32 v60, v0
	v_mov_b32_e32 v61, v0
	v_mov_b32_e32 v62, v0
	v_mov_b32_e32 v63, v0
	v_add_u32_e32 v222, v238, v230
	v_add_u32_e32 v223, v238, v231
	v_add_u32_e32 v241, v238, v232
	v_add_u32_e32 v242, v238, v233
	s_sub_i32 s101, s78, s97
	s_ashr_i32 s101, s101, 6
	s_add_i32 s98, s33, -3
	s_add_i32 s99, s82, -1
	s_add_i32 s100, s74, s97
	s_sub_i32 s100, s100, 63
	v_mov_b32_e32 v166, v160
	v_mov_b32_e32 v167, v161
	v_mov_b32_e32 v168, v162
	v_mov_b32_e32 v169, v163
	v_mov_b32_e32 v162, v156
	v_mov_b32_e32 v163, v157
	v_mov_b32_e32 v164, v158
	v_mov_b32_e32 v165, v159
	v_mov_b32_e32 v174, v152
	v_mov_b32_e32 v175, v153
	v_mov_b32_e32 v176, v154
	v_mov_b32_e32 v177, v155
	v_mov_b32_e32 v170, v148
	v_mov_b32_e32 v171, v149
	v_mov_b32_e32 v172, v150
	v_mov_b32_e32 v173, v151
	s_cmp_ge_i32 s72, s73
	s_mov_b64 s[0:1], -1
	s_cbranch_scc0 .LBB0_321

.LBB0_323:
	s_and_b32 s1, s79, 0x18000
	s_xor_b32 s0, s1, 0x10000
	v_add_u32_e32 v85, s0, v222
	v_add_u32_e32 v254, s0, v223
	v_add_u32_e32 v255, s0, v241
	v_add_u32_e32 v84, s0, v242
	ds_read_b128 v[80:83], v85 offset:16384
	ds_read_b128 v[202:205], v254 offset:16384
	ds_read_b128 v[194:197], v255 offset:16384
	ds_read_b128 v[186:189], v84 offset:16384
	ds_read_b128 v[198:201], v85 offset:20480
	ds_read_b128 v[190:193], v254 offset:20480
	ds_read_b128 v[246:249], v255 offset:20480
	ds_read_b128 v[250:253], v84 offset:20480
	s_cmp_ge_i32 s72, s98
	s_cbranch_scc1 .LBB0_325
	s_add_i32 m0, s1, s94
	s_add_i32 s4, s90, s1
	global_load_lds_dwordx4 v[220:221], off
	s_mov_b32 m0, s4
	s_add_i32 s4, s1, s66
	global_load_lds_dwordx4 v[218:219], off
	s_mov_b32 m0, s4
	v_lshl_add_u64 v[218:219], v[218:219], 0, s[88:89]
	global_load_lds_dwordx4 v[224:225], off
	global_load_lds_dwordx4 v[224:225], off offset:1024
	v_lshl_add_u64 v[220:221], v[220:221], 0, s[88:89]
	v_lshl_add_u64 v[224:225], v[224:225], 0, s[92:93]
.LBB0_325:
	s_waitcnt lgkmcnt(0)
	v_mfma_f32_32x32x16_bf16 v[96:111], v[80:83], v[144:147], v[64:79]
	v_mfma_f32_32x32x16_bf16 v[96:111], v[202:205], v[140:143], v[96:111]
	v_cvt_f32_i32_e32 v156, s100
	v_mfma_f32_32x32x16_bf16 v[96:111], v[194:197], v[136:139], v[96:111]
	v_fma_f32 v254, v208, v156, -v207
	v_mfma_f32_32x32x16_bf16 v[96:111], v[186:189], v[132:135], v[96:111]
	v_add_f32_e32 v255, v237, v254
	s_add_i32 s3, s79, 0xfffe8000
	s_and_b32 s3, s3, 0x18000
	v_add_u32_e32 v158, s3, v235
	v_add_u32_e32 v159, s3, v239
	v_add_u32_e32 v160, s3, v236
	v_add_u32_e32 v161, s3, v234
	ds_read_b64_tr_b16 v[182:183], v158 offset:32768
	ds_read_b64_tr_b16 v[184:185], v158 offset:34816
	ds_read_b64_tr_b16 v[178:179], v159 offset:32768
	ds_read_b64_tr_b16 v[180:181], v159 offset:34816
	ds_read_b64_tr_b16 v[148:149], v160 offset:32768
	ds_read_b64_tr_b16 v[150:151], v160 offset:34816
	ds_read_b64_tr_b16 v[152:153], v161 offset:32768
	ds_read_b64_tr_b16 v[154:155], v161 offset:34816
	v_mfma_f32_32x32x16_bf16 v[80:95], v[198:201], v[144:147], v[64:79]
	v_add_f32_e32 v96, v254, v96
	v_exp_f32_e32 v96, v96
	v_add_f32_e32 v97, v254, v97
	v_exp_f32_e32 v97, v97
	v_add_f32_e32 v98, v254, v98
	v_exp_f32_e32 v98, v98
	v_add_f32_e32 v99, v254, v99
	v_exp_f32_e32 v99, v99
	v_mfma_f32_32x32x16_bf16 v[80:95], v[190:193], v[140:143], v[80:95]
	v_add_f32_e32 v100, v254, v100
	v_exp_f32_e32 v100, v100
	v_add_f32_e32 v101, v254, v101
	v_exp_f32_e32 v101, v101
	v_add_f32_e32 v102, v254, v102
	v_exp_f32_e32 v102, v102
	v_add_f32_e32 v103, v254, v103
	v_exp_f32_e32 v103, v103
	v_mfma_f32_32x32x16_bf16 v[80:95], v[246:249], v[136:139], v[80:95]
	v_add_f32_e32 v104, v254, v104
	v_exp_f32_e32 v104, v104
	v_add_f32_e32 v105, v254, v105
	v_exp_f32_e32 v105, v105
	v_add_f32_e32 v106, v254, v106
	v_exp_f32_e32 v106, v106
	v_add_f32_e32 v107, v254, v107
	v_exp_f32_e32 v107, v107
	v_mfma_f32_32x32x16_bf16 v[80:95], v[250:253], v[132:135], v[80:95]
	v_add_f32_e32 v108, v254, v108
	v_exp_f32_e32 v108, v108
	v_add_f32_e32 v109, v254, v109
	v_exp_f32_e32 v109, v109
	v_add_f32_e32 v110, v254, v110
	v_exp_f32_e32 v110, v110
	v_add_f32_e32 v111, v254, v111
	v_exp_f32_e32 v111, v111
	s_cmp_le_i32 s72, s101
	s_cbranch_scc1 .LBB0_327
	s_lshl_b32 s4, s72, 6
	v_subrev_u32_e32 v156, s4, v240
	v_cmp_gt_i32_e64 s[60:61], 26, v156
	v_cmp_gt_i32_e64 s[62:63], 27, v156
	v_cmp_gt_i32_e64 s[58:59], 25, v156
	s_and_b64 s[60:61], s[62:63], s[60:61]
	v_cmp_gt_i32_e64 s[56:57], 24, v156
	s_and_b64 s[58:59], s[60:61], s[58:59]
	v_cmp_gt_i32_e64 s[54:55], 19, v156
	s_and_b64 s[56:57], s[58:59], s[56:57]
	v_cmp_gt_i32_e64 s[52:53], 18, v156
	s_and_b64 s[54:55], s[56:57], s[54:55]
	v_cmp_gt_i32_e64 s[50:51], 17, v156
	s_and_b64 s[52:53], s[54:55], s[52:53]
	v_cmp_gt_i32_e64 s[48:49], 16, v156
	s_and_b64 s[50:51], s[52:53], s[50:51]
	v_cmp_gt_i32_e64 s[46:47], 11, v156
	s_and_b64 s[48:49], s[50:51], s[48:49]
	v_cmp_gt_i32_e64 s[44:45], 10, v156
	s_and_b64 s[46:47], s[48:49], s[46:47]
	v_cmp_gt_i32_e64 s[42:43], 9, v156
	s_and_b64 s[44:45], s[46:47], s[44:45]
	v_cmp_gt_i32_e64 s[40:41], 8, v156
	s_and_b64 s[42:43], s[44:45], s[42:43]
	v_cmp_gt_i32_e64 s[38:39], 3, v156
	s_and_b64 s[40:41], s[42:43], s[40:41]
	v_cmp_gt_i32_e64 s[36:37], 2, v156
	s_and_b64 s[38:39], s[40:41], s[38:39]
	v_cmp_gt_i32_e64 s[34:35], 1, v156
	s_and_b64 s[36:37], s[38:39], s[36:37]
	v_cmp_gt_i32_e64 s[30:31], 0, v156
	s_and_b64 s[34:35], s[36:37], s[34:35]
	s_and_b64 s[30:31], s[34:35], s[30:31]
	v_cmp_gt_i32_e64 s[28:29], 58, v156
	v_cndmask_b32_e64 v96, v96, v113, s[30:31]
	v_cmp_gt_i32_e64 s[30:31], 59, v156
	v_cmp_gt_i32_e64 s[26:27], 57, v156
	s_and_b64 s[28:29], s[30:31], s[28:29]
	v_cmp_gt_i32_e64 s[24:25], 56, v156
	s_and_b64 s[26:27], s[28:29], s[26:27]
	v_cmp_gt_i32_e64 s[22:23], 51, v156
	s_and_b64 s[24:25], s[26:27], s[24:25]
	v_cmp_gt_i32_e64 s[20:21], 50, v156
	s_and_b64 s[22:23], s[24:25], s[22:23]
	v_cmp_gt_i32_e64 s[18:19], 49, v156
	s_and_b64 s[20:21], s[22:23], s[20:21]
	v_cmp_gt_i32_e64 s[16:17], 48, v156
	s_and_b64 s[18:19], s[20:21], s[18:19]
	v_cmp_gt_i32_e64 s[14:15], 43, v156
	s_and_b64 s[16:17], s[18:19], s[16:17]
	v_cmp_gt_i32_e64 s[12:13], 42, v156
	s_and_b64 s[14:15], s[16:17], s[14:15]
	v_cmp_gt_i32_e64 s[10:11], 41, v156
	s_and_b64 s[12:13], s[14:15], s[12:13]
	v_cmp_gt_i32_e64 s[8:9], 40, v156
	s_and_b64 s[10:11], s[12:13], s[10:11]
	v_cmp_gt_i32_e64 s[6:7], 35, v156
	s_and_b64 s[8:9], s[10:11], s[8:9]
	v_cmp_gt_i32_e64 s[4:5], 34, v156
	s_and_b64 s[6:7], s[8:9], s[6:7]
	v_cmp_gt_i32_e64 s[0:1], 33, v156
	s_and_b64 s[4:5], s[6:7], s[4:5]
	v_cmp_gt_i32_e32 vcc, 32, v156
	s_and_b64 s[0:1], s[4:5], s[0:1]
	s_and_b64 vcc, s[0:1], vcc
	v_cndmask_b32_e64 v111, v111, v113, s[62:63]
	v_cndmask_b32_e64 v110, v110, v113, s[60:61]
	v_cndmask_b32_e64 v109, v109, v113, s[58:59]
	v_cndmask_b32_e64 v108, v108, v113, s[56:57]
	v_cndmask_b32_e64 v107, v107, v113, s[54:55]
	v_cndmask_b32_e64 v106, v106, v113, s[52:53]
	v_cndmask_b32_e64 v105, v105, v113, s[50:51]
	v_cndmask_b32_e64 v104, v104, v113, s[48:49]
	v_cndmask_b32_e64 v103, v103, v113, s[46:47]
	v_cndmask_b32_e64 v102, v102, v113, s[44:45]
	v_cndmask_b32_e64 v101, v101, v113, s[42:43]
	v_cndmask_b32_e64 v100, v100, v113, s[40:41]
	v_cndmask_b32_e64 v99, v99, v113, s[38:39]
	v_cndmask_b32_e64 v98, v98, v113, s[36:37]
	v_cndmask_b32_e64 v97, v97, v113, s[34:35]
	v_cndmask_b32_e64 v95, v95, v228, s[30:31]
	v_cndmask_b32_e64 v94, v94, v228, s[28:29]
	v_cndmask_b32_e64 v93, v93, v228, s[26:27]
	v_cndmask_b32_e64 v92, v92, v228, s[24:25]
	v_cndmask_b32_e64 v91, v91, v228, s[22:23]
	v_cndmask_b32_e64 v90, v90, v228, s[20:21]
	v_cndmask_b32_e64 v89, v89, v228, s[18:19]
	v_cndmask_b32_e64 v88, v88, v228, s[16:17]
	v_cndmask_b32_e64 v87, v87, v228, s[14:15]
	v_cndmask_b32_e64 v86, v86, v228, s[12:13]
	v_cndmask_b32_e64 v85, v85, v228, s[10:11]
	v_cndmask_b32_e64 v84, v84, v228, s[8:9]
	v_cndmask_b32_e64 v83, v83, v228, s[6:7]
	v_cndmask_b32_e64 v82, v82, v228, s[4:5]
	v_cndmask_b32_e64 v81, v81, v228, s[0:1]
	v_cndmask_b32_e32 v80, v80, v228, vcc
.LBB0_327:
	s_waitcnt lgkmcnt(4)
	v_mfma_f32_32x32x16_bf16 v[48:63], v[182:185], v[174:177], v[48:63]
	v_add_f32_e32 v190, v255, v80
	v_exp_f32_e32 v190, v190
	ds_read_b64_tr_b16 v[246:247], v158 offset:36864
	ds_read_b64_tr_b16 v[248:249], v158 offset:38912
	v_add_f32_e32 v157, v190, v96
	v_mfma_f32_32x32x16_bf16 v[32:47], v[178:181], v[174:177], v[32:47]
	v_add_f32_e32 v191, v255, v81
	v_exp_f32_e32 v191, v191
	ds_read_b64_tr_b16 v[250:251], v159 offset:36864
	ds_read_b64_tr_b16 v[252:253], v159 offset:38912
	v_add_f32_e32 v156, v191, v97
	v_add_f32_e32 v157, v156, v157
	s_waitcnt lgkmcnt(4)
	v_mfma_f32_32x32x16_bf16 v[16:31], v[148:151], v[174:177], v[16:31]
	v_add_f32_e32 v192, v255, v82
	v_exp_f32_e32 v192, v192
	ds_read_b64_tr_b16 v[182:183], v160 offset:36864
	ds_read_b64_tr_b16 v[184:185], v160 offset:38912
	v_add_f32_e32 v156, v192, v98
	v_add_f32_e32 v157, v156, v157
	v_mfma_f32_32x32x16_bf16 v[0:15], v[152:155], v[174:177], v[0:15]
	v_add_f32_e32 v193, v255, v83
	v_exp_f32_e32 v193, v193
	ds_read_b64_tr_b16 v[178:179], v161 offset:36864
	ds_read_b64_tr_b16 v[180:181], v161 offset:38912
	v_add_f32_e32 v156, v193, v99
	v_add_f32_e32 v157, v156, v157
	v_cvt_pk_bf16_f32 v174, v96, v97
	s_waitcnt lgkmcnt(4)
	v_mfma_f32_32x32x16_bf16 v[48:63], v[246:249], v[162:165], v[48:63]
	v_add_f32_e32 v194, v255, v84
	v_exp_f32_e32 v194, v194
	ds_read_b64_tr_b16 v[148:149], v158 offset:40960
	ds_read_b64_tr_b16 v[150:151], v158 offset:43008
	v_add_f32_e32 v156, v194, v100
	v_add_f32_e32 v157, v156, v157
	v_cvt_pk_bf16_f32 v175, v98, v99
	v_mfma_f32_32x32x16_bf16 v[32:47], v[250:253], v[162:165], v[32:47]
	v_add_f32_e32 v195, v255, v85
	v_exp_f32_e32 v195, v195
	ds_read_b64_tr_b16 v[152:153], v159 offset:40960
	ds_read_b64_tr_b16 v[154:155], v159 offset:43008
	v_add_f32_e32 v156, v195, v101
	v_add_f32_e32 v157, v156, v157
	v_cvt_pk_bf16_f32 v176, v100, v101
	s_waitcnt lgkmcnt(4)
	v_mfma_f32_32x32x16_bf16 v[16:31], v[182:185], v[162:165], v[16:31]
	v_add_f32_e32 v196, v255, v86
	v_exp_f32_e32 v196, v196
	ds_read_b64_tr_b16 v[246:247], v160 offset:40960
	ds_read_b64_tr_b16 v[248:249], v160 offset:43008
	v_add_f32_e32 v156, v196, v102
	v_add_f32_e32 v157, v156, v157
	v_cvt_pk_bf16_f32 v177, v102, v103
	v_mfma_f32_32x32x16_bf16 v[0:15], v[178:181], v[162:165], v[0:15]
	v_add_f32_e32 v197, v255, v87
	v_exp_f32_e32 v197, v197
	ds_read_b64_tr_b16 v[250:251], v161 offset:40960
	ds_read_b64_tr_b16 v[252:253], v161 offset:43008
	v_add_f32_e32 v156, v197, v103
	v_add_f32_e32 v157, v156, v157
	v_cvt_pk_bf16_f32 v162, v104, v105
	s_waitcnt lgkmcnt(4)
	v_mfma_f32_32x32x16_bf16 v[48:63], v[148:151], v[170:173], v[48:63]
	v_add_f32_e32 v198, v255, v88
	v_exp_f32_e32 v198, v198
	ds_read_b64_tr_b16 v[182:183], v158 offset:45056
	ds_read_b64_tr_b16 v[184:185], v158 offset:47104
	v_add_f32_e32 v156, v198, v104
	v_add_f32_e32 v157, v156, v157
	v_cvt_pk_bf16_f32 v163, v106, v107
	v_mfma_f32_32x32x16_bf16 v[32:47], v[152:155], v[170:173], v[32:47]
	v_add_f32_e32 v199, v255, v89
	v_exp_f32_e32 v199, v199
	ds_read_b64_tr_b16 v[178:179], v159 offset:45056
	ds_read_b64_tr_b16 v[180:181], v159 offset:47104
	v_add_f32_e32 v156, v199, v105
	v_add_f32_e32 v157, v156, v157
	v_cvt_pk_bf16_f32 v164, v108, v109
	s_waitcnt lgkmcnt(4)
	v_mfma_f32_32x32x16_bf16 v[16:31], v[246:249], v[170:173], v[16:31]
	v_add_f32_e32 v200, v255, v90
	v_exp_f32_e32 v200, v200
	ds_read_b64_tr_b16 v[148:149], v160 offset:45056
	ds_read_b64_tr_b16 v[150:151], v160 offset:47104
	v_add_f32_e32 v156, v200, v106
	v_add_f32_e32 v157, v156, v157
	v_cvt_pk_bf16_f32 v165, v110, v111
	v_mfma_f32_32x32x16_bf16 v[0:15], v[250:253], v[170:173], v[0:15]
	v_add_f32_e32 v201, v255, v91
	v_exp_f32_e32 v201, v201
	ds_read_b64_tr_b16 v[152:153], v161 offset:45056
	ds_read_b64_tr_b16 v[154:155], v161 offset:47104
	v_add_f32_e32 v156, v201, v107
	v_add_f32_e32 v157, v156, v157
	v_cvt_pk_bf16_f32 v170, v190, v191
	s_waitcnt lgkmcnt(4)
	v_mfma_f32_32x32x16_bf16 v[48:63], v[182:185], v[166:169], v[48:63]
	v_add_f32_e32 v202, v255, v92
	v_exp_f32_e32 v202, v202
	v_cvt_pk_bf16_f32 v171, v192, v193
	v_add_f32_e32 v156, v202, v108
	v_add_f32_e32 v157, v156, v157
	v_mfma_f32_32x32x16_bf16 v[32:47], v[178:181], v[166:169], v[32:47]
	v_add_f32_e32 v203, v255, v93
	v_exp_f32_e32 v203, v203
	v_cvt_pk_bf16_f32 v172, v194, v195
	v_add_f32_e32 v156, v203, v109
	v_add_f32_e32 v157, v156, v157
	s_waitcnt lgkmcnt(0)
	v_mfma_f32_32x32x16_bf16 v[16:31], v[148:151], v[166:169], v[16:31]
	v_add_f32_e32 v204, v255, v94
	v_exp_f32_e32 v204, v204
	v_cvt_pk_bf16_f32 v173, v196, v197
	v_add_f32_e32 v156, v204, v110
	v_add_f32_e32 v157, v156, v157
	v_mfma_f32_32x32x16_bf16 v[0:15], v[152:155], v[166:169], v[0:15]
	v_add_f32_e32 v205, v255, v95
	v_exp_f32_e32 v205, v205
	v_cvt_pk_bf16_f32 v166, v198, v199
	v_add_f32_e32 v156, v205, v111
	v_add_f32_e32 v157, v156, v157
	v_cvt_pk_bf16_f32 v167, v200, v201
	v_cvt_pk_bf16_f32 v168, v202, v203
	v_cvt_pk_bf16_f32 v169, v204, v205
	s_add_i32 s72, s72, 1
	s_add_i32 s79, s79, 0x8000
	s_add_i32 s100, s100, 64
	v_add_f32_e32 v229, v229, v157
	s_cmp_ge_i32 s72, s99
	s_cbranch_scc1 .LBB0_332
	s_cmp_ge_i32 s72, s73
	s_cbranch_scc1 .Lk_last
	s_waitcnt vmcnt(4) lgkmcnt(0)
	s_barrier
	s_branch .LBB0_323
